# plus: conv LayerNorm wave sums via DPP and permlane swaps instead of ds_bpermute chains
# speedup vs baseline: 1.0068x; 1.0004x over previous
; __device__ __forceinline__ unsigned f2bf(float f) { unsigned u = __builtin_bit_cast(unsigned, f); return (u + 0x7fffu + ((u >> 16) & 1u)) >> 16; }
; __device__ __forceinline__ float sigmoidf_(float x) { return __builtin_amdgcn_rcpf(1.0f + __builtin_amdgcn_exp2f(-x * LOG2E)); }
; __device__ __forceinline__ float wave_sum(float v) {
; #pragma unroll
;     for (int o = 1; o < 64; o <<= 1) v += __shfl_xor(v, o);
;     return v;
; }
; __device__ __forceinline__ void conv_unit(const Ctx& C0, const Params& p, int l, int unit) {
;     ...
;     for (int q = 0; q < 4; ++q) {
;         const int tl = C.wave * 4 + q; float xv[8]; float s = 0.f;
; #pragma unroll
;         for (int i = 0; i < 8; ++i) { xv[i] = U[tl * 512 + C.lane + 64 * i]; s += xv[i]; }
;         const float mean = wave_sum(s) * (1.f / 512.f); float s2 = 0.f;
; #pragma unroll
;         for (int i = 0; i < 8; ++i) { xv[i] -= mean; s2 += xv[i] * xv[i]; }
;         const float rstd = 1.0f / sqrtf(wave_sum(s2) * (1.f / 512.f) + EPS);
; #pragma unroll
;         for (int i = 0; i < 8; ++i) { const int ch = C.lane + 64 * i; const float y = xv[i] * rstd * gl[ch] + bl[ch]; Y[(size_t)(t0 + tl) * 512 + ch] = (bf16)f2bf(y * sigmoidf_(y)); }
;     }
.LBB0_315:
	v_add_u32_e32 v4, s8, v0
	ds_read2st64_b32 v[10:11], v4 offset1:1
	ds_read2st64_b32 v[8:9], v4 offset0:2 offset1:3
	ds_read2st64_b32 v[6:7], v4 offset0:4 offset1:5
	s_ashr_i32 s21, s20, 31
	s_addk_i32 s8, 0x800
	s_waitcnt lgkmcnt(2)
	v_add_f32_e32 v5, 0, v10
	v_add_f32_e32 v5, v5, v11
	s_waitcnt lgkmcnt(1)
	v_add_f32_e32 v5, v5, v8
	v_add_f32_e32 v5, v5, v9
	s_waitcnt lgkmcnt(0)
	v_add_f32_e32 v5, v5, v6
	v_add_f32_e32 v34, v5, v7
	ds_read2st64_b32 v[4:5], v4 offset0:6 offset1:7
	s_waitcnt lgkmcnt(0)
	v_add_f32_e32 v34, v34, v4
	v_add_f32_e32 v34, v34, v5
	s_nop 1
	v_add_f32_dpp v34, v34, v34 quad_perm:[1,0,3,2] row_mask:0xf bank_mask:0xf
	s_nop 1
	v_add_f32_dpp v34, v34, v34 quad_perm:[2,3,0,1] row_mask:0xf bank_mask:0xf
	s_nop 1
	v_add_f32_dpp v34, v34, v34 row_ror:4 row_mask:0xf bank_mask:0xf
	s_nop 1
	v_add_f32_dpp v34, v34, v34 row_ror:8 row_mask:0xf bank_mask:0xf
	v_mov_b32_e32 v35, v34
	s_nop 1
	v_permlane16_swap_b32_e32 v34, v35
	v_add_f32_e32 v34, v34, v35
	v_mov_b32_e32 v35, v34
	s_nop 1
	v_permlane32_swap_b32_e32 v34, v35
	v_add_f32_e32 v34, v34, v35
	v_fmac_f32_e32 v11, 0xbb000000, v34
	v_fmamk_f32 v10, v34, 0xbb000000, v10
	v_mul_f32_e32 v35, v11, v11
	v_fmac_f32_e32 v35, v10, v10
	v_fmamk_f32 v8, v34, 0xbb000000, v8
	v_fmac_f32_e32 v35, v8, v8
	v_fmac_f32_e32 v9, 0xbb000000, v34
	v_fmac_f32_e32 v35, v9, v9
	v_fmamk_f32 v6, v34, 0xbb000000, v6
	v_fmac_f32_e32 v35, v6, v6
	v_fmac_f32_e32 v7, 0xbb000000, v34
	v_fmac_f32_e32 v35, v7, v7
	v_fmamk_f32 v4, v34, 0xbb000000, v4
	v_fmac_f32_e32 v35, v4, v4
	v_fmac_f32_e32 v5, 0xbb000000, v34
	v_fmac_f32_e32 v35, v5, v5
	s_nop 1
	v_add_f32_dpp v34, v35, v35 quad_perm:[1,0,3,2] row_mask:0xf bank_mask:0xf
	s_nop 1
	v_add_f32_dpp v34, v34, v34 quad_perm:[2,3,0,1] row_mask:0xf bank_mask:0xf
	s_nop 1
	v_add_f32_dpp v34, v34, v34 row_ror:4 row_mask:0xf bank_mask:0xf
	s_nop 1
	v_add_f32_dpp v34, v34, v34 row_ror:8 row_mask:0xf bank_mask:0xf
	v_mov_b32_e32 v35, v34
	s_nop 1
	v_permlane16_swap_b32_e32 v34, v35
	v_add_f32_e32 v34, v34, v35
	v_mov_b32_e32 v35, v34
	s_nop 1
	v_permlane32_swap_b32_e32 v34, v35
	v_add_f32_e32 v34, v34, v35
	v_fmamk_f32 v34, v34, 0x3b000000, v175
	v_cmp_gt_f32_e32 vcc, s84, v34
	v_mul_f32_e32 v35, 0x4f800000, v34
	s_nop 0
	v_cndmask_b32_e32 v34, v34, v35, vcc
	v_sqrt_f32_e32 v35, v34
	s_nop 0
	v_add_u32_e32 v36, -1, v35
	v_fma_f32 v37, -v36, v35, v34
	v_cmp_ge_f32_e64 s[0:1], 0, v37
	v_add_u32_e32 v37, 1, v35
	s_nop 0
	v_cndmask_b32_e64 v36, v35, v36, s[0:1]
	v_fma_f32 v35, -v37, v35, v34
	v_cmp_lt_f32_e64 s[0:1], 0, v35
	s_nop 1
	v_cndmask_b32_e64 v35, v36, v37, s[0:1]
	v_mul_f32_e32 v36, 0x37800000, v35
	v_cndmask_b32_e32 v35, v35, v36, vcc
	v_cmp_class_f32_e32 vcc, v34, v176
	s_nop 1
	v_cndmask_b32_e32 v34, v35, v34, vcc
	v_div_scale_f32 v35, s[0:1], v34, v34, 1.0
	v_rcp_f32_e32 v36, v35
	s_lshl_b64 s[0:1], s[20:21], 10
	s_add_i32 s20, s20, 1
	s_cmpk_lg_i32 s8, 0x2000
	v_fma_f32 v37, -v35, v36, 1.0
	v_fmac_f32_e32 v36, v37, v36
	v_div_scale_f32 v37, vcc, 1.0, v34, 1.0
	v_mul_f32_e32 v38, v37, v36
	v_fma_f32 v39, -v35, v38, v37
	v_fmac_f32_e32 v38, v39, v36
	v_fma_f32 v35, -v35, v38, v37
	v_div_fmas_f32 v35, v35, v36, v38
	v_div_fixup_f32 v36, v35, v34, 1.0
	v_mul_f32_e32 v10, v10, v36
	v_fma_f32 v10, v12, v10, v20
	v_mul_f32_e32 v34, 0xbfb8aa3b, v10
	v_exp_f32_e32 v34, v34
	v_mul_f32_e32 v8, v8, v36
	v_fma_f32 v8, v14, v8, v22
	v_mul_f32_e32 v6, v6, v36
	v_add_f32_e32 v34, 1.0, v34
	v_rcp_f32_e32 v34, v34
	v_fma_f32 v6, v16, v6, v24
	v_mul_f32_e32 v4, v4, v36
	v_fma_f32 v4, v18, v4, v26
	v_mul_f32_e32 v10, v10, v34
	v_bfe_u32 v34, v10, 16, 1
	v_add3_u32 v10, v10, v34, s80
	v_lshl_add_u64 v[34:35], v[2:3], 0, s[0:1]
	global_store_short_d16_hi v[34:35], v10, off
	v_mul_f32_e32 v10, v11, v36
	v_fma_f32 v10, v13, v10, v21
	v_mul_f32_e32 v11, 0xbfb8aa3b, v10
	v_exp_f32_e32 v11, v11
	s_nop 0
	v_add_f32_e32 v11, 1.0, v11
	v_rcp_f32_e32 v11, v11
	s_nop 0
	v_mul_f32_e32 v10, v10, v11
	v_bfe_u32 v11, v10, 16, 1
	v_add3_u32 v10, v10, v11, s80
	global_store_short_d16_hi v[34:35], v10, off offset:128
	v_mul_f32_e32 v10, 0xbfb8aa3b, v8
	v_exp_f32_e32 v10, v10
	s_nop 0
	v_add_f32_e32 v10, 1.0, v10
	v_rcp_f32_e32 v10, v10
	s_nop 0
	v_mul_f32_e32 v8, v8, v10
	v_bfe_u32 v10, v8, 16, 1
	v_add3_u32 v8, v8, v10, s80
	global_store_short_d16_hi v[34:35], v8, off offset:256
	v_mul_f32_e32 v8, v9, v36
	v_fma_f32 v8, v15, v8, v23
	v_mul_f32_e32 v9, 0xbfb8aa3b, v8
	v_exp_f32_e32 v9, v9
	s_nop 0
	v_add_f32_e32 v9, 1.0, v9
	v_rcp_f32_e32 v9, v9
	s_nop 0
	v_mul_f32_e32 v8, v8, v9
	v_bfe_u32 v9, v8, 16, 1
	v_add3_u32 v8, v8, v9, s80
	global_store_short_d16_hi v[34:35], v8, off offset:384
	v_mul_f32_e32 v8, 0xbfb8aa3b, v6
	v_exp_f32_e32 v8, v8
	s_nop 0
	v_add_f32_e32 v8, 1.0, v8
	v_rcp_f32_e32 v8, v8
	s_nop 0
	v_mul_f32_e32 v6, v6, v8
	v_bfe_u32 v8, v6, 16, 1
	v_add3_u32 v6, v6, v8, s80
	global_store_short_d16_hi v[34:35], v6, off offset:512
	v_mul_f32_e32 v6, v7, v36
	v_fma_f32 v6, v17, v6, v25
	v_mul_f32_e32 v7, 0xbfb8aa3b, v6
	v_exp_f32_e32 v7, v7
	s_nop 0
	v_add_f32_e32 v7, 1.0, v7
	v_rcp_f32_e32 v7, v7
	s_nop 0
	v_mul_f32_e32 v6, v6, v7
	v_bfe_u32 v7, v6, 16, 1
	v_add3_u32 v6, v6, v7, s80
	global_store_short_d16_hi v[34:35], v6, off offset:640
	v_mul_f32_e32 v6, 0xbfb8aa3b, v4
	v_exp_f32_e32 v6, v6
	s_nop 0
	v_add_f32_e32 v6, 1.0, v6
	v_rcp_f32_e32 v6, v6
	s_nop 0
	v_mul_f32_e32 v4, v4, v6
	v_bfe_u32 v6, v4, 16, 1
	v_add3_u32 v4, v4, v6, s80
	global_store_short_d16_hi v[34:35], v4, off offset:768
	v_mul_f32_e32 v4, v5, v36
	v_fma_f32 v4, v19, v4, v27
	v_mul_f32_e32 v5, 0xbfb8aa3b, v4
	v_exp_f32_e32 v5, v5
	s_nop 0
	v_add_f32_e32 v5, 1.0, v5
	v_rcp_f32_e32 v5, v5
	s_nop 0
	v_mul_f32_e32 v4, v4, v5
	v_bfe_u32 v5, v4, 16, 1
	v_add3_u32 v4, v4, v5, s80
	global_store_short_d16_hi v[34:35], v4, off offset:896
	s_cbranch_scc1 .LBB0_315
	v_readlane_b32 s0, v254, 44
	s_add_i32 s37, s37, s96
	s_add_i32 s36, s36, s0
	s_cmpk_gt_i32 s37, 0x3ff
	v_readlane_b32 s59, v254, 54
	s_barrier
	s_cbranch_scc0 .LBB0_280
